# v16 counted waits + mode-A next-tile QK takes -mhat C operand from live registers (8 v_mov_b64 per tile removed)
# baseline (speedup 1.0000x reference)
; #define SBAR() __builtin_amdgcn_sched_barrier(0)
; template <int DQK, int DV, int MODE>
; __device__ __forceinline__ void attn_item(LAS unsigned char* lds, int item, const AttnCtx& cx) {
;     ...
;     auto do_qk = [&](int j, bool vpre) {
;         const unsigned kaddr = (unsigned)(size_t)(lds + (j % NST) * SB + koff) + r * KP + 16 * h;
;         const unsigned va = vaddr_of(j);
;         bf16x8 kfr[1][4];
;         K_ISSUE(0, 0);
; #pragma unroll
;         for (int kb = 0; kb < NQF / 2; ++kb) {
;             LGKM0(); SBAR();
;             if (kb == 0) { if (MODE == 1) { s0 = MFMA32(kfr[0][0], qf[0], cin0); s1 = MFMA32(kfr[0][1], qf[0], cin1); } else { s0 = MFMA32(kfr[0][0], qf[0], negm); s1 = MFMA32(kfr[0][1], qf[0], negm); } }
;             else { s0 = MFMA32(kfr[0][0], qf[2 * kb], s0); s1 = MFMA32(kfr[0][1], qf[2 * kb], s1); }
;             s0 = MFMA32(kfr[0][2], qf[2 * kb + 1], s0); s1 = MFMA32(kfr[0][3], qf[2 * kb + 1], s1);
;             SBAR();
;             if (kb + 1 < NQF / 2) K_ISSUE(0, kb + 1); else if (vpre) V_ISSUE(va, 0, 0);
;         }
;     ...
;         for (int i = 0; i < 16; ++i) { s0[i] = fast_exp2(s0[i]); s1[i] = fast_exp2(s1[i]); }
;         u32x4 w;
;         w.x = pk2(s0[0], s0[1]); w.y = pk2(s0[2], s0[3]); w.z = pk2(s0[4], s0[5]); w.w = pk2(s0[6], s0[7]); pa[0][0] = __builtin_bit_cast(bf16x8, w);
;         w.x = pk2(s0[8], s0[9]); w.y = pk2(s0[10], s0[11]); w.z = pk2(s0[12], s0[13]); w.w = pk2(s0[14], s0[15]); pa[0][1] = __builtin_bit_cast(bf16x8, w);
;         w.x = pk2(s1[0], s1[1]); w.y = pk2(s1[2], s1[3]); w.z = pk2(s1[4], s1[5]); w.w = pk2(s1[6], s1[7]); pa[1][0] = __builtin_bit_cast(bf16x8, w);
;         w.x = pk2(s1[8], s1[9]); w.y = pk2(s1[10], s1[11]); w.z = pk2(s1[12], s1[13]); w.w = pk2(s1[14], s1[15]); pa[1][1] = __builtin_bit_cast(bf16x8, w);
;     };
;     auto do_pv = [&](unsigned va) {
; #pragma unroll
;         for (int k4 = 0; k4 < 4; ++k4) Lacc = MFMA32(ones8, pa[k4 >> 1][k4 & 1], Lacc);
; #pragma unroll
;         for (int d = 0; d < NDV; ++d) {
;             LGKM0(); SBAR();
; #pragma unroll
;             for (int k4 = 0; k4 < 4; ++k4) {
;                 const bf16x8 vf = __builtin_shufflevector(vlo[d & 1][k4], vhi[d & 1][k4], 0, 1, 2, 3, 4, 5, 6, 7);
;                 O[d] = MFMA32(vf, pa[k4 >> 1][k4 & 1], O[d]);
;             }
;             SBAR();
;             if (d + 1 < NDV) V_ISSUE(va, (d + 1) & 1, d + 1);
.LBB0_256:
.LBB0_257:
	s_mov_b32 s90, s88
	s_mov_b32 s91, s88
	s_mov_b32 s89, s88
	v_mov_b64_e32 v[228:229], s[90:91]
	v_exp_f32_e32 v82, v82
	v_exp_f32_e32 v83, v83
	v_exp_f32_e32 v84, v84
	v_exp_f32_e32 v85, v85
	v_exp_f32_e32 v86, v86
	v_exp_f32_e32 v87, v87
	v_exp_f32_e32 v88, v88
	v_exp_f32_e32 v89, v89
	v_mov_b64_e32 v[226:227], s[88:89]
	v_cvt_pk_bf16_f32 v230, v82, v83
	v_cvt_pk_bf16_f32 v231, v84, v85
	v_cvt_pk_bf16_f32 v232, v86, v87
	v_cvt_pk_bf16_f32 v233, v88, v89
	v_exp_f32_e32 v90, v90
	v_exp_f32_e32 v91, v91
	v_mfma_f32_32x32x16_bf16 v[66:81], v[226:229], v[230:233], v[66:81]
	v_exp_f32_e32 v92, v92
	v_exp_f32_e32 v93, v93
	v_exp_f32_e32 v94, v94
	v_exp_f32_e32 v95, v95
	v_exp_f32_e32 v96, v96
	v_exp_f32_e32 v97, v97
	v_cvt_pk_bf16_f32 v234, v90, v91
	v_cvt_pk_bf16_f32 v235, v92, v93
	v_cvt_pk_bf16_f32 v236, v94, v95
	v_cvt_pk_bf16_f32 v237, v96, v97
	v_exp_f32_e32 v98, v98
	v_exp_f32_e32 v99, v99
	v_mfma_f32_32x32x16_bf16 v[66:81], v[226:229], v[234:237], v[66:81]
	v_exp_f32_e32 v100, v100
	v_exp_f32_e32 v101, v101
	v_exp_f32_e32 v102, v102
	v_exp_f32_e32 v103, v103
	v_exp_f32_e32 v104, v104
	v_exp_f32_e32 v105, v105
	v_cvt_pk_bf16_f32 v238, v98, v99
	v_cvt_pk_bf16_f32 v239, v100, v101
	v_cvt_pk_bf16_f32 v240, v102, v103
	v_cvt_pk_bf16_f32 v241, v104, v105
	v_exp_f32_e32 v106, v106
	v_exp_f32_e32 v107, v107
	v_mfma_f32_32x32x16_bf16 v[66:81], v[226:229], v[238:241], v[66:81]
	v_exp_f32_e32 v108, v108
	v_exp_f32_e32 v109, v109
	v_exp_f32_e32 v110, v110
	v_exp_f32_e32 v111, v111
	v_exp_f32_e32 v112, v112
	v_exp_f32_e32 v113, v113
	v_cvt_pk_bf16_f32 v242, v106, v107
	v_cvt_pk_bf16_f32 v243, v108, v109
	v_cvt_pk_bf16_f32 v244, v110, v111
	v_cvt_pk_bf16_f32 v245, v112, v113
	s_and_b32 s3, s82, 3
	s_mul_i32 s3, s3, 0x9800
	v_mfma_f32_32x32x16_bf16 v[66:81], v[226:229], v[242:245], v[66:81]
	s_waitcnt lgkmcnt(0)
	s_add_i32 s3, s3, 0
	s_addk_i32 s3, 0x4800
	v_add_u32_e32 v213, s3, v203
	v_mfma_f32_32x32x16_bf16 v[50:65], v[162:165], v[230:233], v[50:65]
	v_mfma_f32_32x32x16_bf16 v[50:65], v[166:169], v[234:237], v[50:65]
	v_mfma_f32_32x32x16_bf16 v[50:65], v[170:173], v[238:241], v[50:65]
	v_mfma_f32_32x32x16_bf16 v[50:65], v[174:177], v[242:245], v[50:65]
	ds_read_b64_tr_b16 v[162:163], v213 offset:64
	ds_read_b64_tr_b16 v[164:165], v213 offset:2624
	ds_read_b64_tr_b16 v[166:167], v213 offset:5184
	ds_read_b64_tr_b16 v[168:169], v213 offset:7744
	ds_read_b64_tr_b16 v[170:171], v213 offset:10304
	ds_read_b64_tr_b16 v[172:173], v213 offset:12864
	ds_read_b64_tr_b16 v[174:175], v213 offset:15424
	ds_read_b64_tr_b16 v[176:177], v213 offset:17984
	s_waitcnt lgkmcnt(6)
	s_nop 0
	s_nop 0
	v_mfma_f32_32x32x16_bf16 v[34:49], v[162:165], v[230:233], v[34:49]
	s_waitcnt lgkmcnt(4)
	v_mfma_f32_32x32x16_bf16 v[34:49], v[166:169], v[234:237], v[34:49]
	s_waitcnt lgkmcnt(2)
	v_mfma_f32_32x32x16_bf16 v[34:49], v[170:173], v[238:241], v[34:49]
	s_waitcnt lgkmcnt(0)
	v_mfma_f32_32x32x16_bf16 v[34:49], v[174:177], v[242:245], v[34:49]
	ds_read_b64_tr_b16 v[162:163], v213 offset:128
	ds_read_b64_tr_b16 v[164:165], v213 offset:2688
	ds_read_b64_tr_b16 v[166:167], v213 offset:5248
	ds_read_b64_tr_b16 v[168:169], v213 offset:7808
	ds_read_b64_tr_b16 v[170:171], v213 offset:10368
	ds_read_b64_tr_b16 v[172:173], v213 offset:12928
	ds_read_b64_tr_b16 v[174:175], v213 offset:15488
	ds_read_b64_tr_b16 v[176:177], v213 offset:18048
	s_waitcnt lgkmcnt(6)
	s_nop 0
	s_nop 0
	v_mfma_f32_32x32x16_bf16 v[18:33], v[162:165], v[230:233], v[18:33]
	s_waitcnt lgkmcnt(4)
	v_mfma_f32_32x32x16_bf16 v[18:33], v[166:169], v[234:237], v[18:33]
	s_waitcnt lgkmcnt(2)
	v_mfma_f32_32x32x16_bf16 v[18:33], v[170:173], v[238:241], v[18:33]
	s_waitcnt lgkmcnt(0)
	v_mfma_f32_32x32x16_bf16 v[18:33], v[174:177], v[242:245], v[18:33]
	ds_read_b64_tr_b16 v[226:227], v213 offset:192
	ds_read_b64_tr_b16 v[228:229], v213 offset:2752
	ds_read_b64_tr_b16 v[246:247], v213 offset:5312
	ds_read_b64_tr_b16 v[248:249], v213 offset:7872
	ds_read_b64_tr_b16 v[222:223], v213 offset:10432
	ds_read_b64_tr_b16 v[224:225], v213 offset:12992
	ds_read_b64_tr_b16 v[214:215], v213 offset:15552
	ds_read_b64_tr_b16 v[216:217], v213 offset:18112
	s_waitcnt lgkmcnt(6)
	s_nop 0
	s_nop 0
	v_mfma_f32_32x32x16_bf16 v[2:17], v[226:229], v[230:233], v[2:17]
	s_waitcnt lgkmcnt(4)
	v_mfma_f32_32x32x16_bf16 v[2:17], v[246:249], v[234:237], v[2:17]
	s_waitcnt lgkmcnt(2)
	v_mfma_f32_32x32x16_bf16 v[2:17], v[222:225], v[238:241], v[2:17]
	s_waitcnt lgkmcnt(0)
	v_mfma_f32_32x32x16_bf16 v[2:17], v[214:217], v[242:245], v[2:17]
	s_add_i32 s82, s82, 1
	s_cmp_ge_u32 s82, s83
	s_cselect_b64 s[50:51], -1, 0
	s_or_b64 s[50:51], s[24:25], s[50:51]
	s_and_b64 vcc, exec, s[50:51]
	s_cbranch_vccnz .LBB0_200
	s_and_b32 s3, s82, 3
	s_mul_i32 s3, s3, 0x9800
	s_add_i32 s3, s77, s3
	v_add_u32_e32 v213, s3, v202
	ds_read_b128 v[98:101], v213 offset:0
	ds_read_b128 v[102:105], v213 offset:4608
	ds_read_b128 v[106:109], v213 offset:32
	ds_read_b128 v[110:113], v213 offset:4640
	s_waitcnt lgkmcnt(3)
	s_nop 0
	s_nop 0
	v_mfma_f32_32x32x16_bf16 v[82:97], v[98:101], v[146:149], v[114:129]
	s_waitcnt lgkmcnt(2)
	v_mfma_f32_32x32x16_bf16 v[130:145], v[102:105], v[146:149], v[114:129]
	s_waitcnt lgkmcnt(1)
	v_mfma_f32_32x32x16_bf16 v[82:97], v[106:109], v[150:153], v[82:97]
	s_waitcnt lgkmcnt(0)
	v_mfma_f32_32x32x16_bf16 v[130:145], v[110:113], v[150:153], v[130:145]
	ds_read_b128 v[98:101], v213 offset:64
	ds_read_b128 v[102:105], v213 offset:4672
	ds_read_b128 v[106:109], v213 offset:96
	ds_read_b128 v[110:113], v213 offset:4704
	s_waitcnt lgkmcnt(3)
	s_nop 0
	s_nop 0
	v_mfma_f32_32x32x16_bf16 v[82:97], v[98:101], v[154:157], v[82:97]
	s_waitcnt lgkmcnt(2)
	v_mfma_f32_32x32x16_bf16 v[130:145], v[102:105], v[154:157], v[130:145]
	s_waitcnt lgkmcnt(1)
	v_mfma_f32_32x32x16_bf16 v[82:97], v[106:109], v[158:161], v[82:97]
	s_waitcnt lgkmcnt(0)
	v_mfma_f32_32x32x16_bf16 v[130:145], v[110:113], v[158:161], v[130:145]
	s_nop 11
	v_mov_b32_e32 v98, v130
	v_mov_b32_e32 v99, v131
	v_mov_b32_e32 v100, v132
	v_mov_b32_e32 v101, v133
	v_mov_b32_e32 v102, v134
	v_mov_b32_e32 v103, v135
	v_mov_b32_e32 v104, v136
	v_mov_b32_e32 v105, v137
	v_mov_b32_e32 v106, v138
	v_mov_b32_e32 v107, v139
	v_mov_b32_e32 v108, v140
	v_mov_b32_e32 v109, v141
	v_mov_b32_e32 v110, v142
	v_mov_b32_e32 v111, v143
	v_mov_b32_e32 v112, v144
	v_mov_b32_e32 v113, v145
	s_branch .LBB0_200
